# weight-conversion chunks in P1/P7 GEMM tails and P5 queue use the hand-written LDS-free transposer; 4 chunks per idle workgroup in P1 tail
# speedup vs baseline: 1.0038x; 1.0038x over previous
.LBB0_479:
	s_cmpk_lg_i32 s26, 0x100
	s_cselect_b64 s[4:5], -1, 0
	s_cmpk_lt_i32 s2, 0x88
	s_cselect_b64 s[8:9], -1, 0
	s_or_b64 s[4:5], s[8:9], s[4:5]
	s_and_b64 vcc, exec, s[4:5]
	s_cbranch_vccnz .LBB0_555
	s_waitcnt vmcnt(0)
	s_mov_b32 s98, 0
.Ltr1_loop:
	s_add_i32 s99, s2, 0x1b8
	s_add_i32 s99, s99, s98
	s_movk_i32 s74, 0x588
	s_movk_i32 s75, 0x120
	s_mov_b32 s76, 0x20700000
	s_movk_i32 s77, 0x100
	s_movk_i32 s78, 0x1000
	s_cmpk_lt_u32 s99, 0x588
	s_cselect_b32 s74, 0x548, s74
	s_cselect_b32 s75, 0xc0, s75
	s_cselect_b32 s76, 0x1f700000, s76
	s_cselect_b32 s77, 0x800, s77
	s_cselect_b32 s78, 0x1000, s78
	s_cmpk_lt_u32 s99, 0x548
	s_cselect_b32 s74, 0x508, s74
	s_cselect_b32 s75, 0x60, s75
	s_cselect_b32 s76, 0x1e700000, s76
	s_cselect_b32 s77, 0x800, s77
	s_cselect_b32 s78, 0x1000, s78
	s_cmpk_lt_u32 s99, 0x508
	s_cselect_b32 s74, 0x488, s74
	s_cselect_b32 s75, 0x118, s75
	s_cselect_b32 s76, 0x1c700000, s76
	s_cselect_b32 s77, 0x1000, s77
	s_cselect_b32 s78, 0x1000, s78
	s_cmpk_lt_u32 s99, 0x488
	s_cselect_b32 s74, 0x408, s74
	s_cselect_b32 s75, 0xc8, s75
	s_cselect_b32 s76, 0x1a700000, s76
	s_cselect_b32 s77, 0x1000, s77
	s_cselect_b32 s78, 0x1000, s78
	s_cmpk_lt_u32 s99, 0x408
	s_cselect_b32 s74, 0x2b0, s74
	s_cselect_b32 s75, 0x108, s75
	s_cselect_b32 s76, 0x15100000, s76
	s_cselect_b32 s77, 0x2b00, s77
	s_cselect_b32 s78, 0x1000, s78
	s_cmpk_lt_u32 s99, 0x2b0
	s_cselect_b32 s74, 0x0, s74
	s_cselect_b32 s75, 0xf0, s75
	s_cselect_b32 s76, 0xa500000, s76
	s_cselect_b32 s77, 0x1000, s77
	s_cselect_b32 s78, 0x5600, s78
	s_load_dwordx2 s[36:37], s[0:1], s75
	s_sub_i32 s79, s99, s74
	s_lshl_b32 s79, s79, 6
	s_lshl_b32 s86, s90, 3
	s_add_i32 s79, s79, s86
	s_mul_i32 s80, s79, 0xbe84
	s_lshr_b32 s80, s80, 25
	s_mul_i32 s81, s80, 0x2b0
	s_sub_i32 s81, s79, s81
	s_lshr_b32 s86, s79, 7
	s_and_b32 s72, s79, 0x7f
	s_cmpk_lt_u32 s99, 0x2b0
	s_cselect_b32 s80, s80, s86
	s_cselect_b32 s81, s81, s72
	s_lshl_b32 s80, s80, 6
	s_lshl_b32 s81, s81, 5
	s_mul_i32 s86, s80, s78
	s_add_i32 s86, s86, s81
	s_lshl_b32 s86, s86, 2
	s_lshl_b32 s64, s78, 2
	s_mov_b32 s65, 0
	s_lshl_b32 s66, s77, 1
	s_mov_b32 s67, 0
	s_lshl_b32 s68, s77, 2
	s_mov_b32 s69, 0
	s_mul_i32 s70, s77, 6
	s_mov_b32 s71, 0
	s_add_u32 s62, s30, s76
	s_addc_u32 s63, s31, 0
	s_lshl_b32 s79, s80, 1
	v_lshrrev_b32_e32 v160, 3, v162
	v_lshl_add_u32 v160, v160, 2, s81
	v_mul_lo_u32 v160, v160, s66
	v_and_b32_e32 v161, 7, v162
	v_lshl_add_u32 v160, v161, 4, v160
	v_add_u32_e32 v160, s79, v160
	v_mov_b32_e32 v161, 0
	v_lshl_add_u64 v[136:137], s[62:63], 0, v[160:161]
	v_and_b32_e32 v160, 7, v162
	s_lshl_b32 s79, s78, 5
	v_mul_lo_u32 v160, v160, s79
	v_lshrrev_b32_e32 v118, 3, v162
	v_lshl_add_u32 v160, v118, 4, v160
	s_waitcnt lgkmcnt(0)
	s_add_u32 s36, s36, s86
	s_addc_u32 s37, s37, 0
	v_lshl_add_u64 v[166:167], s[36:37], 0, v[160:161]
	s_lshl_b32 s72, s77, 6
	s_mov_b32 s73, 0
	v_mov_b64_e32 v[118:119], v[166:167]
	global_load_dwordx4 v[120:123], v[118:119], off nt
	v_lshl_add_u64 v[118:119], v[118:119], 0, s[64:65]
	global_load_dwordx4 v[124:127], v[118:119], off nt
	v_lshl_add_u64 v[118:119], v[118:119], 0, s[64:65]
	global_load_dwordx4 v[128:131], v[118:119], off nt
	v_lshl_add_u64 v[118:119], v[118:119], 0, s[64:65]
	global_load_dwordx4 v[132:135], v[118:119], off nt
	v_lshl_add_u64 v[118:119], v[118:119], 0, s[64:65]
	global_load_dwordx4 v[140:143], v[118:119], off nt
	v_lshl_add_u64 v[118:119], v[118:119], 0, s[64:65]
	global_load_dwordx4 v[144:147], v[118:119], off nt
	v_lshl_add_u64 v[118:119], v[118:119], 0, s[64:65]
	global_load_dwordx4 v[148:151], v[118:119], off nt
	v_lshl_add_u64 v[118:119], v[118:119], 0, s[64:65]
	global_load_dwordx4 v[152:155], v[118:119], off nt
	v_mov_b64_e32 v[118:119], v[166:167]
	global_load_dwordx4 v[156:159], v[118:119], off offset:128 nt
	v_lshl_add_u64 v[118:119], v[118:119], 0, s[64:65]
	global_load_dwordx4 v[168:171], v[118:119], off offset:128 nt
	v_lshl_add_u64 v[118:119], v[118:119], 0, s[64:65]
	global_load_dwordx4 v[172:175], v[118:119], off offset:128 nt
	v_lshl_add_u64 v[118:119], v[118:119], 0, s[64:65]
	global_load_dwordx4 v[176:179], v[118:119], off offset:128 nt
	v_lshl_add_u64 v[118:119], v[118:119], 0, s[64:65]
	global_load_dwordx4 v[180:183], v[118:119], off offset:128 nt
	v_lshl_add_u64 v[118:119], v[118:119], 0, s[64:65]
	global_load_dwordx4 v[184:187], v[118:119], off offset:128 nt
	v_lshl_add_u64 v[118:119], v[118:119], 0, s[64:65]
	global_load_dwordx4 v[188:191], v[118:119], off offset:128 nt
	v_lshl_add_u64 v[118:119], v[118:119], 0, s[64:65]
	global_load_dwordx4 v[192:195], v[118:119], off offset:128 nt
	v_mov_b64_e32 v[118:119], v[166:167]
	global_load_dwordx4 v[196:199], v[118:119], off offset:256 nt
	v_lshl_add_u64 v[118:119], v[118:119], 0, s[64:65]
	global_load_dwordx4 v[200:203], v[118:119], off offset:256 nt
	v_lshl_add_u64 v[118:119], v[118:119], 0, s[64:65]
	global_load_dwordx4 v[204:207], v[118:119], off offset:256 nt
	v_lshl_add_u64 v[118:119], v[118:119], 0, s[64:65]
	global_load_dwordx4 v[208:211], v[118:119], off offset:256 nt
	v_lshl_add_u64 v[118:119], v[118:119], 0, s[64:65]
	global_load_dwordx4 v[212:215], v[118:119], off offset:256 nt
	v_lshl_add_u64 v[118:119], v[118:119], 0, s[64:65]
	global_load_dwordx4 v[216:219], v[118:119], off offset:256 nt
	v_lshl_add_u64 v[118:119], v[118:119], 0, s[64:65]
	global_load_dwordx4 v[220:223], v[118:119], off offset:256 nt
	v_lshl_add_u64 v[118:119], v[118:119], 0, s[64:65]
	global_load_dwordx4 v[224:227], v[118:119], off offset:256 nt
	s_waitcnt vmcnt(16)
	v_cvt_pk_bf16_f32 v228, v120, v124
	v_cvt_pk_bf16_f32 v229, v128, v132
	v_cvt_pk_bf16_f32 v230, v140, v144
	v_cvt_pk_bf16_f32 v231, v148, v152
	v_cvt_pk_bf16_f32 v232, v121, v125
	v_cvt_pk_bf16_f32 v233, v129, v133
	v_cvt_pk_bf16_f32 v234, v141, v145
	v_cvt_pk_bf16_f32 v235, v149, v153
	global_store_dwordx4 v[136:137], v[228:231], off
	v_lshl_add_u64 v[160:161], v[136:137], 0, s[66:67]
	global_store_dwordx4 v[160:161], v[232:235], off
	s_nop 1
	v_cvt_pk_bf16_f32 v228, v122, v126
	v_cvt_pk_bf16_f32 v229, v130, v134
	v_cvt_pk_bf16_f32 v230, v142, v146
	v_cvt_pk_bf16_f32 v231, v150, v154
	v_cvt_pk_bf16_f32 v232, v123, v127
	v_cvt_pk_bf16_f32 v233, v131, v135
	v_cvt_pk_bf16_f32 v234, v143, v147
	v_cvt_pk_bf16_f32 v235, v151, v155
	v_lshl_add_u64 v[160:161], v[136:137], 0, s[68:69]
	global_store_dwordx4 v[160:161], v[228:231], off
	v_lshl_add_u64 v[160:161], v[136:137], 0, s[70:71]
	global_store_dwordx4 v[160:161], v[232:235], off
	v_lshl_add_u64 v[136:137], v[136:137], 0, s[72:73]
	v_mov_b64_e32 v[118:119], v[166:167]
	global_load_dwordx4 v[120:123], v[118:119], off offset:384 nt
	v_lshl_add_u64 v[118:119], v[118:119], 0, s[64:65]
	global_load_dwordx4 v[124:127], v[118:119], off offset:384 nt
	v_lshl_add_u64 v[118:119], v[118:119], 0, s[64:65]
	global_load_dwordx4 v[128:131], v[118:119], off offset:384 nt
	v_lshl_add_u64 v[118:119], v[118:119], 0, s[64:65]
	global_load_dwordx4 v[132:135], v[118:119], off offset:384 nt
	v_lshl_add_u64 v[118:119], v[118:119], 0, s[64:65]
	global_load_dwordx4 v[140:143], v[118:119], off offset:384 nt
	v_lshl_add_u64 v[118:119], v[118:119], 0, s[64:65]
	global_load_dwordx4 v[144:147], v[118:119], off offset:384 nt
	v_lshl_add_u64 v[118:119], v[118:119], 0, s[64:65]
	global_load_dwordx4 v[148:151], v[118:119], off offset:384 nt
	v_lshl_add_u64 v[118:119], v[118:119], 0, s[64:65]
	global_load_dwordx4 v[152:155], v[118:119], off offset:384 nt
	s_waitcnt vmcnt(20)
	v_cvt_pk_bf16_f32 v228, v156, v168
	v_cvt_pk_bf16_f32 v229, v172, v176
	v_cvt_pk_bf16_f32 v230, v180, v184
	v_cvt_pk_bf16_f32 v231, v188, v192
	v_cvt_pk_bf16_f32 v232, v157, v169
	v_cvt_pk_bf16_f32 v233, v173, v177
	v_cvt_pk_bf16_f32 v234, v181, v185
	v_cvt_pk_bf16_f32 v235, v189, v193
	global_store_dwordx4 v[136:137], v[228:231], off
	v_lshl_add_u64 v[160:161], v[136:137], 0, s[66:67]
	global_store_dwordx4 v[160:161], v[232:235], off
	s_nop 1
	v_cvt_pk_bf16_f32 v228, v158, v170
	v_cvt_pk_bf16_f32 v229, v174, v178
	v_cvt_pk_bf16_f32 v230, v182, v186
	v_cvt_pk_bf16_f32 v231, v190, v194
	v_cvt_pk_bf16_f32 v232, v159, v171
	v_cvt_pk_bf16_f32 v233, v175, v179
	v_cvt_pk_bf16_f32 v234, v183, v187
	v_cvt_pk_bf16_f32 v235, v191, v195
	v_lshl_add_u64 v[160:161], v[136:137], 0, s[68:69]
	global_store_dwordx4 v[160:161], v[228:231], off
	v_lshl_add_u64 v[160:161], v[136:137], 0, s[70:71]
	global_store_dwordx4 v[160:161], v[232:235], off
	v_lshl_add_u64 v[136:137], v[136:137], 0, s[72:73]
	v_mov_b64_e32 v[118:119], v[166:167]
	global_load_dwordx4 v[156:159], v[118:119], off offset:512 nt
	v_lshl_add_u64 v[118:119], v[118:119], 0, s[64:65]
	global_load_dwordx4 v[168:171], v[118:119], off offset:512 nt
	v_lshl_add_u64 v[118:119], v[118:119], 0, s[64:65]
	global_load_dwordx4 v[172:175], v[118:119], off offset:512 nt
	v_lshl_add_u64 v[118:119], v[118:119], 0, s[64:65]
	global_load_dwordx4 v[176:179], v[118:119], off offset:512 nt
	v_lshl_add_u64 v[118:119], v[118:119], 0, s[64:65]
	global_load_dwordx4 v[180:183], v[118:119], off offset:512 nt
	v_lshl_add_u64 v[118:119], v[118:119], 0, s[64:65]
	global_load_dwordx4 v[184:187], v[118:119], off offset:512 nt
	v_lshl_add_u64 v[118:119], v[118:119], 0, s[64:65]
	global_load_dwordx4 v[188:191], v[118:119], off offset:512 nt
	v_lshl_add_u64 v[118:119], v[118:119], 0, s[64:65]
	global_load_dwordx4 v[192:195], v[118:119], off offset:512 nt
	s_waitcnt vmcnt(24)
	v_cvt_pk_bf16_f32 v228, v196, v200
	v_cvt_pk_bf16_f32 v229, v204, v208
	v_cvt_pk_bf16_f32 v230, v212, v216
	v_cvt_pk_bf16_f32 v231, v220, v224
	v_cvt_pk_bf16_f32 v232, v197, v201
	v_cvt_pk_bf16_f32 v233, v205, v209
	v_cvt_pk_bf16_f32 v234, v213, v217
	v_cvt_pk_bf16_f32 v235, v221, v225
	global_store_dwordx4 v[136:137], v[228:231], off
	v_lshl_add_u64 v[160:161], v[136:137], 0, s[66:67]
	global_store_dwordx4 v[160:161], v[232:235], off
	s_nop 1
	v_cvt_pk_bf16_f32 v228, v198, v202
	v_cvt_pk_bf16_f32 v229, v206, v210
	v_cvt_pk_bf16_f32 v230, v214, v218
	v_cvt_pk_bf16_f32 v231, v222, v226
	v_cvt_pk_bf16_f32 v232, v199, v203
	v_cvt_pk_bf16_f32 v233, v207, v211
	v_cvt_pk_bf16_f32 v234, v215, v219
	v_cvt_pk_bf16_f32 v235, v223, v227
	v_lshl_add_u64 v[160:161], v[136:137], 0, s[68:69]
	global_store_dwordx4 v[160:161], v[228:231], off
	v_lshl_add_u64 v[160:161], v[136:137], 0, s[70:71]
	global_store_dwordx4 v[160:161], v[232:235], off
	v_lshl_add_u64 v[136:137], v[136:137], 0, s[72:73]
	v_mov_b64_e32 v[118:119], v[166:167]
	global_load_dwordx4 v[196:199], v[118:119], off offset:640 nt
	v_lshl_add_u64 v[118:119], v[118:119], 0, s[64:65]
	global_load_dwordx4 v[200:203], v[118:119], off offset:640 nt
	v_lshl_add_u64 v[118:119], v[118:119], 0, s[64:65]
	global_load_dwordx4 v[204:207], v[118:119], off offset:640 nt
	v_lshl_add_u64 v[118:119], v[118:119], 0, s[64:65]
	global_load_dwordx4 v[208:211], v[118:119], off offset:640 nt
	v_lshl_add_u64 v[118:119], v[118:119], 0, s[64:65]
	global_load_dwordx4 v[212:215], v[118:119], off offset:640 nt
	v_lshl_add_u64 v[118:119], v[118:119], 0, s[64:65]
	global_load_dwordx4 v[216:219], v[118:119], off offset:640 nt
	v_lshl_add_u64 v[118:119], v[118:119], 0, s[64:65]
	global_load_dwordx4 v[220:223], v[118:119], off offset:640 nt
	v_lshl_add_u64 v[118:119], v[118:119], 0, s[64:65]
	global_load_dwordx4 v[224:227], v[118:119], off offset:640 nt
	s_waitcnt vmcnt(24)
	v_cvt_pk_bf16_f32 v228, v120, v124
	v_cvt_pk_bf16_f32 v229, v128, v132
	v_cvt_pk_bf16_f32 v230, v140, v144
	v_cvt_pk_bf16_f32 v231, v148, v152
	v_cvt_pk_bf16_f32 v232, v121, v125
	v_cvt_pk_bf16_f32 v233, v129, v133
	v_cvt_pk_bf16_f32 v234, v141, v145
	v_cvt_pk_bf16_f32 v235, v149, v153
	global_store_dwordx4 v[136:137], v[228:231], off
	v_lshl_add_u64 v[160:161], v[136:137], 0, s[66:67]
	global_store_dwordx4 v[160:161], v[232:235], off
	s_nop 1
	v_cvt_pk_bf16_f32 v228, v122, v126
	v_cvt_pk_bf16_f32 v229, v130, v134
	v_cvt_pk_bf16_f32 v230, v142, v146
	v_cvt_pk_bf16_f32 v231, v150, v154
	v_cvt_pk_bf16_f32 v232, v123, v127
	v_cvt_pk_bf16_f32 v233, v131, v135
	v_cvt_pk_bf16_f32 v234, v143, v147
	v_cvt_pk_bf16_f32 v235, v151, v155
	v_lshl_add_u64 v[160:161], v[136:137], 0, s[68:69]
	global_store_dwordx4 v[160:161], v[228:231], off
	v_lshl_add_u64 v[160:161], v[136:137], 0, s[70:71]
	global_store_dwordx4 v[160:161], v[232:235], off
	v_lshl_add_u64 v[136:137], v[136:137], 0, s[72:73]
	v_mov_b64_e32 v[118:119], v[166:167]
	global_load_dwordx4 v[120:123], v[118:119], off offset:768 nt
	v_lshl_add_u64 v[118:119], v[118:119], 0, s[64:65]
	global_load_dwordx4 v[124:127], v[118:119], off offset:768 nt
	v_lshl_add_u64 v[118:119], v[118:119], 0, s[64:65]
	global_load_dwordx4 v[128:131], v[118:119], off offset:768 nt
	v_lshl_add_u64 v[118:119], v[118:119], 0, s[64:65]
	global_load_dwordx4 v[132:135], v[118:119], off offset:768 nt
	v_lshl_add_u64 v[118:119], v[118:119], 0, s[64:65]
	global_load_dwordx4 v[140:143], v[118:119], off offset:768 nt
	v_lshl_add_u64 v[118:119], v[118:119], 0, s[64:65]
	global_load_dwordx4 v[144:147], v[118:119], off offset:768 nt
	v_lshl_add_u64 v[118:119], v[118:119], 0, s[64:65]
	global_load_dwordx4 v[148:151], v[118:119], off offset:768 nt
	v_lshl_add_u64 v[118:119], v[118:119], 0, s[64:65]
	global_load_dwordx4 v[152:155], v[118:119], off offset:768 nt
	s_waitcnt vmcnt(24)
	v_cvt_pk_bf16_f32 v228, v156, v168
	v_cvt_pk_bf16_f32 v229, v172, v176
	v_cvt_pk_bf16_f32 v230, v180, v184
	v_cvt_pk_bf16_f32 v231, v188, v192
	v_cvt_pk_bf16_f32 v232, v157, v169
	v_cvt_pk_bf16_f32 v233, v173, v177
	v_cvt_pk_bf16_f32 v234, v181, v185
	v_cvt_pk_bf16_f32 v235, v189, v193
	global_store_dwordx4 v[136:137], v[228:231], off
	v_lshl_add_u64 v[160:161], v[136:137], 0, s[66:67]
	global_store_dwordx4 v[160:161], v[232:235], off
	s_nop 1
	v_cvt_pk_bf16_f32 v228, v158, v170
	v_cvt_pk_bf16_f32 v229, v174, v178
	v_cvt_pk_bf16_f32 v230, v182, v186
	v_cvt_pk_bf16_f32 v231, v190, v194
	v_cvt_pk_bf16_f32 v232, v159, v171
	v_cvt_pk_bf16_f32 v233, v175, v179
	v_cvt_pk_bf16_f32 v234, v183, v187
	v_cvt_pk_bf16_f32 v235, v191, v195
	v_lshl_add_u64 v[160:161], v[136:137], 0, s[68:69]
	global_store_dwordx4 v[160:161], v[228:231], off
	v_lshl_add_u64 v[160:161], v[136:137], 0, s[70:71]
	global_store_dwordx4 v[160:161], v[232:235], off
	v_lshl_add_u64 v[136:137], v[136:137], 0, s[72:73]
	v_mov_b64_e32 v[118:119], v[166:167]
	global_load_dwordx4 v[156:159], v[118:119], off offset:896 nt
	v_lshl_add_u64 v[118:119], v[118:119], 0, s[64:65]
	global_load_dwordx4 v[168:171], v[118:119], off offset:896 nt
	v_lshl_add_u64 v[118:119], v[118:119], 0, s[64:65]
	global_load_dwordx4 v[172:175], v[118:119], off offset:896 nt
	v_lshl_add_u64 v[118:119], v[118:119], 0, s[64:65]
	global_load_dwordx4 v[176:179], v[118:119], off offset:896 nt
	v_lshl_add_u64 v[118:119], v[118:119], 0, s[64:65]
	global_load_dwordx4 v[180:183], v[118:119], off offset:896 nt
	v_lshl_add_u64 v[118:119], v[118:119], 0, s[64:65]
	global_load_dwordx4 v[184:187], v[118:119], off offset:896 nt
	v_lshl_add_u64 v[118:119], v[118:119], 0, s[64:65]
	global_load_dwordx4 v[188:191], v[118:119], off offset:896 nt
	v_lshl_add_u64 v[118:119], v[118:119], 0, s[64:65]
	global_load_dwordx4 v[192:195], v[118:119], off offset:896 nt
	s_waitcnt vmcnt(24)
	v_cvt_pk_bf16_f32 v228, v196, v200
	v_cvt_pk_bf16_f32 v229, v204, v208
	v_cvt_pk_bf16_f32 v230, v212, v216
	v_cvt_pk_bf16_f32 v231, v220, v224
	v_cvt_pk_bf16_f32 v232, v197, v201
	v_cvt_pk_bf16_f32 v233, v205, v209
	v_cvt_pk_bf16_f32 v234, v213, v217
	v_cvt_pk_bf16_f32 v235, v221, v225
	global_store_dwordx4 v[136:137], v[228:231], off
	v_lshl_add_u64 v[160:161], v[136:137], 0, s[66:67]
	global_store_dwordx4 v[160:161], v[232:235], off
	s_nop 1
	v_cvt_pk_bf16_f32 v228, v198, v202
	v_cvt_pk_bf16_f32 v229, v206, v210
	v_cvt_pk_bf16_f32 v230, v214, v218
	v_cvt_pk_bf16_f32 v231, v222, v226
	v_cvt_pk_bf16_f32 v232, v199, v203
	v_cvt_pk_bf16_f32 v233, v207, v211
	v_cvt_pk_bf16_f32 v234, v215, v219
	v_cvt_pk_bf16_f32 v235, v223, v227
	v_lshl_add_u64 v[160:161], v[136:137], 0, s[68:69]
	global_store_dwordx4 v[160:161], v[228:231], off
	v_lshl_add_u64 v[160:161], v[136:137], 0, s[70:71]
	global_store_dwordx4 v[160:161], v[232:235], off
	v_lshl_add_u64 v[136:137], v[136:137], 0, s[72:73]
	s_waitcnt vmcnt(16)
	v_cvt_pk_bf16_f32 v228, v120, v124
	v_cvt_pk_bf16_f32 v229, v128, v132
	v_cvt_pk_bf16_f32 v230, v140, v144
	v_cvt_pk_bf16_f32 v231, v148, v152
	v_cvt_pk_bf16_f32 v232, v121, v125
	v_cvt_pk_bf16_f32 v233, v129, v133
	v_cvt_pk_bf16_f32 v234, v141, v145
	v_cvt_pk_bf16_f32 v235, v149, v153
	global_store_dwordx4 v[136:137], v[228:231], off
	v_lshl_add_u64 v[160:161], v[136:137], 0, s[66:67]
	global_store_dwordx4 v[160:161], v[232:235], off
	s_nop 1
	v_cvt_pk_bf16_f32 v228, v122, v126
	v_cvt_pk_bf16_f32 v229, v130, v134
	v_cvt_pk_bf16_f32 v230, v142, v146
	v_cvt_pk_bf16_f32 v231, v150, v154
	v_cvt_pk_bf16_f32 v232, v123, v127
	v_cvt_pk_bf16_f32 v233, v131, v135
	v_cvt_pk_bf16_f32 v234, v143, v147
	v_cvt_pk_bf16_f32 v235, v151, v155
	v_lshl_add_u64 v[160:161], v[136:137], 0, s[68:69]
	global_store_dwordx4 v[160:161], v[228:231], off
	v_lshl_add_u64 v[160:161], v[136:137], 0, s[70:71]
	global_store_dwordx4 v[160:161], v[232:235], off
	v_lshl_add_u64 v[136:137], v[136:137], 0, s[72:73]
	s_waitcnt vmcnt(8)
	v_cvt_pk_bf16_f32 v228, v156, v168
	v_cvt_pk_bf16_f32 v229, v172, v176
	v_cvt_pk_bf16_f32 v230, v180, v184
	v_cvt_pk_bf16_f32 v231, v188, v192
	v_cvt_pk_bf16_f32 v232, v157, v169
	v_cvt_pk_bf16_f32 v233, v173, v177
	v_cvt_pk_bf16_f32 v234, v181, v185
	v_cvt_pk_bf16_f32 v235, v189, v193
	global_store_dwordx4 v[136:137], v[228:231], off
	v_lshl_add_u64 v[160:161], v[136:137], 0, s[66:67]
	global_store_dwordx4 v[160:161], v[232:235], off
	s_nop 1
	v_cvt_pk_bf16_f32 v228, v158, v170
	v_cvt_pk_bf16_f32 v229, v174, v178
	v_cvt_pk_bf16_f32 v230, v182, v186
	v_cvt_pk_bf16_f32 v231, v190, v194
	v_cvt_pk_bf16_f32 v232, v159, v171
	v_cvt_pk_bf16_f32 v233, v175, v179
	v_cvt_pk_bf16_f32 v234, v183, v187
	v_cvt_pk_bf16_f32 v235, v191, v195
	v_lshl_add_u64 v[160:161], v[136:137], 0, s[68:69]
	global_store_dwordx4 v[160:161], v[228:231], off
	v_lshl_add_u64 v[160:161], v[136:137], 0, s[70:71]
	global_store_dwordx4 v[160:161], v[232:235], off
	v_lshl_add_u64 v[136:137], v[136:137], 0, s[72:73]
	s_addk_i32 s98, 0x78
	s_cmp_lt_u32 s98, 480
	s_cbranch_scc1 .Ltr1_loop

.LBB0_954:
	s_cmpk_eq_i32 s26, 0x100
	s_movk_i32 s4, 0x170
	s_cselect_b32 s45, s4, 0x590
	s_movk_i32 s4, 0xfc90
	s_cselect_b32 s27, s4, 0xfffff870
	s_movk_i32 s4, 0x220
	s_cselect_b32 s41, s4, 0xfffffe00
	s_movk_i32 s4, 0x1c0
	v_cmp_gt_u32_e32 vcc, s4, v0
	s_movk_i32 s4, 0xffc8
	v_lshrrev_b32_e32 v1, 3, v0
	s_waitcnt vmcnt(0)
	v_cndmask_b32_e32 v2, 0, v0, vcc
	v_mul_u32_u24_e32 v3, 0x493, v2
	v_lshrrev_b32_e32 v7, 16, v3
	v_mad_i32_i24 v8, v7, s4, v2
	v_mov_b32_e32 v2, 0xffffff00
	v_and_b32_e32 v6, 7, v0
	v_mov_b32_e32 v109, 0
	v_lshlrev_b32_e32 v9, 4, v8
	s_movk_i32 s4, 0x7000
	v_lshl_add_u32 v11, v8, 5, v2
	v_add_u32_e32 v2, -16, v8
	v_lshlrev_b32_e32 v108, 8, v1
	v_mad_u32_u24 v112, v7, s4, v9
	v_cmp_gt_u32_e64 s[4:5], 32, v2
	v_lshlrev_b32_e32 v2, 5, v6
	v_lshl_add_u64 v[4:5], s[28:29], 0, v[108:109]
	v_mov_b32_e32 v3, v109
	v_add_u32_e32 v10, 0x200, v9
	v_lshl_add_u64 v[4:5], v[4:5], 0, v[2:3]
	s_mov_b64 s[6:7], 0x19a6fc00
	v_lshrrev_b32_e32 v3, 4, v0
	v_cmp_gt_u32_e64 s[10:11], 48, v8
	v_lshl_add_u64 v[114:115], v[4:5], 0, s[6:7]
	v_lshlrev_b32_e32 v5, 8, v3
	v_lshlrev_b32_e32 v116, 13, v3
	v_cndmask_b32_e64 v3, v10, v11, s[10:11]
	v_cmp_gt_i32_e64 s[10:11], 16, v8
	v_lshrrev_b32_e32 v178, 3, v162
	s_movk_i32 s12, 0x100
	v_cndmask_b32_e64 v3, v3, v9, s[10:11]
	s_movk_i32 s10, 0x580
	v_lshlrev_b32_e32 v9, 3, v0
	v_mad_u32_u24 v3, v7, s10, v3
	s_lshl_b32 s10, s90, 14
	v_and_b32_e32 v118, 56, v9
	s_add_i32 s10, s10, 0
	v_and_b32_e32 v176, 31, v0
	v_mul_u32_u24_e32 v9, 0x84, v118
	v_lshlrev_b32_e32 v10, 2, v178
	v_lshl_add_u32 v7, v176, 2, s10
	v_add3_u32 v179, s10, v9, v10
	v_cmp_gt_u32_e64 s[10:11], s12, v0
	v_lshlrev_b32_e32 v108, 1, v0
	s_lshl_b32 s12, s90, 2
	v_and_b32_e32 v124, 0x1fc, v164
	v_lshrrev_b32_e32 v186, 7, v0
	s_add_i32 s43, s45, 0x200
	s_addk_i32 s45, 0x600
	s_and_b64 s[14:15], vcc, s[4:5]
	s_lshl_b32 s80, s90, 3
	v_lshl_add_u64 v[122:123], s[46:47], 0, v[108:109]
	s_add_i32 s81, s12, 0
	v_lshlrev_b32_e32 v14, 14, v186
	v_lshlrev_b32_e32 v108, 2, v124
	v_and_b32_e32 v4, 60, v164
	s_cmp_lt_u32 s91, 64
	v_add3_u32 v187, 0, v14, v108
	v_or_b32_e32 v14, 0x200, v0
	s_movk_i32 s20, 0xffe0
	v_lshlrev_b32_e32 v13, 2, v4
	s_cselect_b64 s[24:25], -1, 0
	s_cmpk_lt_u32 s91, 0x80
	v_lshrrev_b32_e32 v190, 7, v14
	v_lshlrev_b32_e32 v106, 6, v1
	v_add_u32_e32 v107, 0, v2
	v_lshlrev_b32_e32 v119, 1, v1
	v_add3_u32 v125, 0, v5, v13
	v_add_u32_e32 v5, 16, v3
	v_mov_b32_e32 v165, v109
	s_cselect_b64 s[50:51], -1, 0
	s_cmpk_lt_u32 s91, 0xc0
	v_lshlrev_b32_e32 v14, 11, v190
	v_cndmask_b32_e32 v3, -1, v3, vcc
	v_mad_i32_i24 v2, v6, s20, v2
	v_lshlrev_b32_e32 v1, 2, v1
	v_lshl_add_u64 v[120:121], s[56:57], 0, v[164:165]
	s_cselect_b64 s[56:57], -1, 0
	s_cmpk_lt_u32 s91, 0x100
	v_add3_u32 v191, 0, v14, v108
	v_mov_b32_e32 v14, 0xb000
	v_cmp_lt_i32_e32 vcc, -1, v3
	v_add3_u32 v1, v2, v1, 0
	s_cselect_b64 s[58:59], -1, 0
	s_cmpk_lt_u32 s91, 0x140
	v_cndmask_b32_e64 v5, -1, v5, s[14:15]
	v_cndmask_b32_e32 v15, v14, v3, vcc
	v_add_u32_e32 v3, 0x5800, v3
	v_add_u32_e32 v194, 0xb040, v1
	v_add_u32_e32 v197, 0xc040, v1
	v_and_b32_e32 v1, 0x7f, v0
	v_lshrrev_b32_e32 v177, 5, v162
	v_add_u32_e32 v165, 0, v164
	v_lshlrev_b32_e32 v184, 5, v162
	s_cselect_b64 s[60:61], -1, 0
	s_cmpk_lt_u32 s91, 0x180
	v_lshl_add_u64 v[126:127], s[28:29], 0, v[108:109]
	s_movk_i32 s36, 0xc800
	v_mov_b32_e32 v16, 0xb010
	v_cmp_lt_i32_e64 s[14:15], -1, v5
	v_cndmask_b32_e32 v14, v14, v3, vcc
	v_add_u32_e32 v3, 0x5800, v5
	v_lshlrev_b32_e32 v108, 4, v1
	v_lshl_add_u32 v1, v186, 8, 0
	v_writelane_b32 v242, s82, 5
	v_mad_i32_i24 v12, v6, s20, v107
	s_movk_i32 s6, 0x80
	s_movk_i32 s8, 0x7f
	v_mul_u32_u24_e32 v8, 0x84, v177
	v_mad_u32_u24 v183, v0, 28, v165
	v_mul_i32_i24_e32 v9, 0xffffffe4, v0
	v_or_b32_e32 v10, 0x800, v184
	v_or_b32_e32 v11, 0x1000, v184
	v_or_b32_e32 v13, 0x1800, v184
	s_cselect_b64 s[62:63], -1, 0
	s_cmpk_lt_u32 s91, 0x1c0
	v_mad_i32_i24 v188, v186, s36, v187
	v_cndmask_b32_e64 v17, v16, v5, s[14:15]
	v_cndmask_b32_e64 v5, v16, v3, s[14:15]
	v_lshl_add_u64 v[2:3], s[28:29], 0, v[108:109]
	s_mov_b64 s[14:15], 0x9a73400
	v_add_u32_e32 v199, 0x6000, v1
	v_mbcnt_lo_u32_b32 v1, -1, 0
	v_writelane_b32 v242, s83, 6
	v_lshlrev_b32_e32 v110, 3, v6
	s_mov_b32 s21, 0
	v_ashrrev_i32_e32 v113, 31, v112
	v_mul_i32_i24_e32 v111, 0xffffffe0, v6
	v_cmp_gt_u32_e64 s[6:7], s6, v0
	v_cmp_lt_u32_e64 s[8:9], s8, v0
	v_mov_b32_e32 v117, v109
	v_or_b32_e32 v180, 8, v178
	v_or_b32_e32 v181, 16, v178
	v_or_b32_e32 v182, 24, v178
	v_cmp_eq_u32_e64 s[12:13], 0, v162
	s_mul_i32 s82, s90, 28
	v_lshl_add_u32 v185, v162, 2, 0
	s_movk_i32 s83, 0x1000
	s_cselect_b64 s[64:65], -1, 0
	v_add_u32_e32 v189, 0x6500, v188
	v_add_u32_e32 v192, 0x6500, v191
	v_lshlrev_b32_e32 v193, 15, v186
	v_add_u32_e32 v195, 0x580, v107
	v_mad_i32_i24 v196, v6, s20, v119
	v_add_u32_e32 v198, 0x5d80, v107
	v_lshl_add_u64 v[128:129], v[2:3], 0, s[14:15]
	v_lshl_add_u32 v202, v186, 11, 0
	s_add_i32 s84, 0, 0x20140
	s_mov_b64 s[14:15], 0x4000
	v_lshlrev_b32_e32 v130, 2, v4
	v_add_u32_e32 v203, v183, v9
	v_add_u32_e32 v204, s81, v10
	v_add_u32_e32 v205, s81, v11
	v_add_u32_e32 v206, s81, v13
	s_movk_i32 s85, 0x3000
	s_movk_i32 s86, 0xd000
	s_movk_i32 s87, 0xe000
	s_movk_i32 s92, 0xf000
	v_add_u32_e32 v207, 0, v15
	v_add_u32_e32 v208, 0, v17
	v_add_u32_e32 v209, v12, v119
	v_add_u32_e32 v210, 0, v14
	v_add_u32_e32 v211, 0, v5
	v_add_u32_e32 v212, v7, v8
	v_mbcnt_hi_u32_b32 v213, -1, v1
	s_branch .LBB0_957

.LBB0_1239:
	s_cmpk_lg_i32 s26, 0x100
	s_cselect_b64 s[4:5], -1, 0
	s_cmp_lt_i32 s2, 64
	s_cselect_b64 s[8:9], -1, 0
	s_or_b64 s[4:5], s[8:9], s[4:5]
	s_and_b64 vcc, exec, s[4:5]
	s_cbranch_vccnz .LBB0_1315
	s_waitcnt vmcnt(0)
	s_mov_b32 s98, 0
.Ltr7_loop:
	s_add_i32 s99, s2, 0xffffffc0
	s_add_i32 s99, s99, s98
	s_movk_i32 s74, 0x588
	s_movk_i32 s75, 0x120
	s_mov_b32 s76, 0x20700000
	s_movk_i32 s77, 0x100
	s_movk_i32 s78, 0x1000
	s_cmpk_lt_u32 s99, 0x588
	s_cselect_b32 s74, 0x548, s74
	s_cselect_b32 s75, 0xc0, s75
	s_cselect_b32 s76, 0x1f700000, s76
	s_cselect_b32 s77, 0x800, s77
	s_cselect_b32 s78, 0x1000, s78
	s_cmpk_lt_u32 s99, 0x548
	s_cselect_b32 s74, 0x508, s74
	s_cselect_b32 s75, 0x60, s75
	s_cselect_b32 s76, 0x1e700000, s76
	s_cselect_b32 s77, 0x800, s77
	s_cselect_b32 s78, 0x1000, s78
	s_cmpk_lt_u32 s99, 0x508
	s_cselect_b32 s74, 0x488, s74
	s_cselect_b32 s75, 0x118, s75
	s_cselect_b32 s76, 0x1c700000, s76
	s_cselect_b32 s77, 0x1000, s77
	s_cselect_b32 s78, 0x1000, s78
	s_cmpk_lt_u32 s99, 0x488
	s_cselect_b32 s74, 0x408, s74
	s_cselect_b32 s75, 0xc8, s75
	s_cselect_b32 s76, 0x1a700000, s76
	s_cselect_b32 s77, 0x1000, s77
	s_cselect_b32 s78, 0x1000, s78
	s_cmpk_lt_u32 s99, 0x408
	s_cselect_b32 s74, 0x2b0, s74
	s_cselect_b32 s75, 0x108, s75
	s_cselect_b32 s76, 0x15100000, s76
	s_cselect_b32 s77, 0x2b00, s77
	s_cselect_b32 s78, 0x1000, s78
	s_cmpk_lt_u32 s99, 0x2b0
	s_cselect_b32 s74, 0x0, s74
	s_cselect_b32 s75, 0xf0, s75
	s_cselect_b32 s76, 0xa500000, s76
	s_cselect_b32 s77, 0x1000, s77
	s_cselect_b32 s78, 0x5600, s78
	s_load_dwordx2 s[56:57], s[0:1], s75
	s_sub_i32 s79, s99, s74
	s_lshl_b32 s79, s79, 6
	s_lshl_b32 s86, s90, 3
	s_add_i32 s79, s79, s86
	s_mul_i32 s80, s79, 0xbe84
	s_lshr_b32 s80, s80, 25
	s_mul_i32 s81, s80, 0x2b0
	s_sub_i32 s81, s79, s81
	s_lshr_b32 s86, s79, 7
	s_and_b32 s72, s79, 0x7f
	s_cmpk_lt_u32 s99, 0x2b0
	s_cselect_b32 s80, s80, s86
	s_cselect_b32 s81, s81, s72
	s_lshl_b32 s80, s80, 6
	s_lshl_b32 s81, s81, 5
	s_mul_i32 s86, s80, s78
	s_add_i32 s86, s86, s81
	s_lshl_b32 s86, s86, 2
	s_lshl_b32 s64, s78, 2
	s_mov_b32 s65, 0
	s_lshl_b32 s66, s77, 1
	s_mov_b32 s67, 0
	s_lshl_b32 s68, s77, 2
	s_mov_b32 s69, 0
	s_mul_i32 s70, s77, 6
	s_mov_b32 s71, 0
	s_add_u32 s62, s30, s76
	s_addc_u32 s63, s31, 0
	s_lshl_b32 s79, s80, 1
	v_lshrrev_b32_e32 v202, 3, v162
	v_lshl_add_u32 v202, v202, 2, s81
	v_mul_lo_u32 v202, v202, s66
	v_and_b32_e32 v203, 7, v162
	v_lshl_add_u32 v202, v203, 4, v202
	v_add_u32_e32 v202, s79, v202
	v_mov_b32_e32 v203, 0
	v_lshl_add_u64 v[166:167], s[62:63], 0, v[202:203]
	v_and_b32_e32 v202, 7, v162
	s_lshl_b32 s79, s78, 5
	v_mul_lo_u32 v202, v202, s79
	v_lshrrev_b32_e32 v160, 3, v162
	v_lshl_add_u32 v202, v160, 4, v202
	s_waitcnt lgkmcnt(0)
	s_add_u32 s56, s56, s86
	s_addc_u32 s57, s57, 0
	v_lshl_add_u64 v[240:241], s[56:57], 0, v[202:203]
	s_lshl_b32 s72, s77, 6
	s_mov_b32 s73, 0
	v_mov_b64_e32 v[160:161], v[240:241]
	global_load_dwordx4 v[128:131], v[160:161], off nt
	v_lshl_add_u64 v[160:161], v[160:161], 0, s[64:65]
	global_load_dwordx4 v[132:135], v[160:161], off nt
	v_lshl_add_u64 v[160:161], v[160:161], 0, s[64:65]
	global_load_dwordx4 v[136:139], v[160:161], off nt
	v_lshl_add_u64 v[160:161], v[160:161], 0, s[64:65]
	global_load_dwordx4 v[140:143], v[160:161], off nt
	v_lshl_add_u64 v[160:161], v[160:161], 0, s[64:65]
	global_load_dwordx4 v[144:147], v[160:161], off nt
	v_lshl_add_u64 v[160:161], v[160:161], 0, s[64:65]
	global_load_dwordx4 v[148:151], v[160:161], off nt
	v_lshl_add_u64 v[160:161], v[160:161], 0, s[64:65]
	global_load_dwordx4 v[152:155], v[160:161], off nt
	v_lshl_add_u64 v[160:161], v[160:161], 0, s[64:65]
	global_load_dwordx4 v[156:159], v[160:161], off nt
	v_mov_b64_e32 v[160:161], v[240:241]
	global_load_dwordx4 v[168:171], v[160:161], off offset:128 nt
	v_lshl_add_u64 v[160:161], v[160:161], 0, s[64:65]
	global_load_dwordx4 v[172:175], v[160:161], off offset:128 nt
	v_lshl_add_u64 v[160:161], v[160:161], 0, s[64:65]
	global_load_dwordx4 v[176:179], v[160:161], off offset:128 nt
	v_lshl_add_u64 v[160:161], v[160:161], 0, s[64:65]
	global_load_dwordx4 v[180:183], v[160:161], off offset:128 nt
	v_lshl_add_u64 v[160:161], v[160:161], 0, s[64:65]
	global_load_dwordx4 v[184:187], v[160:161], off offset:128 nt
	v_lshl_add_u64 v[160:161], v[160:161], 0, s[64:65]
	global_load_dwordx4 v[188:191], v[160:161], off offset:128 nt
	v_lshl_add_u64 v[160:161], v[160:161], 0, s[64:65]
	global_load_dwordx4 v[192:195], v[160:161], off offset:128 nt
	v_lshl_add_u64 v[160:161], v[160:161], 0, s[64:65]
	global_load_dwordx4 v[196:199], v[160:161], off offset:128 nt
	v_mov_b64_e32 v[160:161], v[240:241]
	global_load_dwordx4 v[204:207], v[160:161], off offset:256 nt
	v_lshl_add_u64 v[160:161], v[160:161], 0, s[64:65]
	global_load_dwordx4 v[208:211], v[160:161], off offset:256 nt
	v_lshl_add_u64 v[160:161], v[160:161], 0, s[64:65]
	global_load_dwordx4 v[212:215], v[160:161], off offset:256 nt
	v_lshl_add_u64 v[160:161], v[160:161], 0, s[64:65]
	global_load_dwordx4 v[216:219], v[160:161], off offset:256 nt
	v_lshl_add_u64 v[160:161], v[160:161], 0, s[64:65]
	global_load_dwordx4 v[220:223], v[160:161], off offset:256 nt
	v_lshl_add_u64 v[160:161], v[160:161], 0, s[64:65]
	global_load_dwordx4 v[224:227], v[160:161], off offset:256 nt
	v_lshl_add_u64 v[160:161], v[160:161], 0, s[64:65]
	global_load_dwordx4 v[228:231], v[160:161], off offset:256 nt
	v_lshl_add_u64 v[160:161], v[160:161], 0, s[64:65]
	global_load_dwordx4 v[232:235], v[160:161], off offset:256 nt
	s_waitcnt vmcnt(16)
	v_cvt_pk_bf16_f32 v236, v128, v132
	v_cvt_pk_bf16_f32 v237, v136, v140
	v_cvt_pk_bf16_f32 v238, v144, v148
	v_cvt_pk_bf16_f32 v239, v152, v156
	v_cvt_pk_bf16_f32 v244, v129, v133
	v_cvt_pk_bf16_f32 v245, v137, v141
	v_cvt_pk_bf16_f32 v246, v145, v149
	v_cvt_pk_bf16_f32 v247, v153, v157
	global_store_dwordx4 v[166:167], v[236:239], off
	v_lshl_add_u64 v[202:203], v[166:167], 0, s[66:67]
	global_store_dwordx4 v[202:203], v[244:247], off
	s_nop 1
	v_cvt_pk_bf16_f32 v236, v130, v134
	v_cvt_pk_bf16_f32 v237, v138, v142
	v_cvt_pk_bf16_f32 v238, v146, v150
	v_cvt_pk_bf16_f32 v239, v154, v158
	v_cvt_pk_bf16_f32 v244, v131, v135
	v_cvt_pk_bf16_f32 v245, v139, v143
	v_cvt_pk_bf16_f32 v246, v147, v151
	v_cvt_pk_bf16_f32 v247, v155, v159
	v_lshl_add_u64 v[202:203], v[166:167], 0, s[68:69]
	global_store_dwordx4 v[202:203], v[236:239], off
	v_lshl_add_u64 v[202:203], v[166:167], 0, s[70:71]
	global_store_dwordx4 v[202:203], v[244:247], off
	v_lshl_add_u64 v[166:167], v[166:167], 0, s[72:73]
	v_mov_b64_e32 v[160:161], v[240:241]
	global_load_dwordx4 v[128:131], v[160:161], off offset:384 nt
	v_lshl_add_u64 v[160:161], v[160:161], 0, s[64:65]
	global_load_dwordx4 v[132:135], v[160:161], off offset:384 nt
	v_lshl_add_u64 v[160:161], v[160:161], 0, s[64:65]
	global_load_dwordx4 v[136:139], v[160:161], off offset:384 nt
	v_lshl_add_u64 v[160:161], v[160:161], 0, s[64:65]
	global_load_dwordx4 v[140:143], v[160:161], off offset:384 nt
	v_lshl_add_u64 v[160:161], v[160:161], 0, s[64:65]
	global_load_dwordx4 v[144:147], v[160:161], off offset:384 nt
	v_lshl_add_u64 v[160:161], v[160:161], 0, s[64:65]
	global_load_dwordx4 v[148:151], v[160:161], off offset:384 nt
	v_lshl_add_u64 v[160:161], v[160:161], 0, s[64:65]
	global_load_dwordx4 v[152:155], v[160:161], off offset:384 nt
	v_lshl_add_u64 v[160:161], v[160:161], 0, s[64:65]
	global_load_dwordx4 v[156:159], v[160:161], off offset:384 nt
	s_waitcnt vmcnt(20)
	v_cvt_pk_bf16_f32 v236, v168, v172
	v_cvt_pk_bf16_f32 v237, v176, v180
	v_cvt_pk_bf16_f32 v238, v184, v188
	v_cvt_pk_bf16_f32 v239, v192, v196
	v_cvt_pk_bf16_f32 v244, v169, v173
	v_cvt_pk_bf16_f32 v245, v177, v181
	v_cvt_pk_bf16_f32 v246, v185, v189
	v_cvt_pk_bf16_f32 v247, v193, v197
	global_store_dwordx4 v[166:167], v[236:239], off
	v_lshl_add_u64 v[202:203], v[166:167], 0, s[66:67]
	global_store_dwordx4 v[202:203], v[244:247], off
	s_nop 1
	v_cvt_pk_bf16_f32 v236, v170, v174
	v_cvt_pk_bf16_f32 v237, v178, v182
	v_cvt_pk_bf16_f32 v238, v186, v190
	v_cvt_pk_bf16_f32 v239, v194, v198
	v_cvt_pk_bf16_f32 v244, v171, v175
	v_cvt_pk_bf16_f32 v245, v179, v183
	v_cvt_pk_bf16_f32 v246, v187, v191
	v_cvt_pk_bf16_f32 v247, v195, v199
	v_lshl_add_u64 v[202:203], v[166:167], 0, s[68:69]
	global_store_dwordx4 v[202:203], v[236:239], off
	v_lshl_add_u64 v[202:203], v[166:167], 0, s[70:71]
	global_store_dwordx4 v[202:203], v[244:247], off
	v_lshl_add_u64 v[166:167], v[166:167], 0, s[72:73]
	v_mov_b64_e32 v[160:161], v[240:241]
	global_load_dwordx4 v[168:171], v[160:161], off offset:512 nt
	v_lshl_add_u64 v[160:161], v[160:161], 0, s[64:65]
	global_load_dwordx4 v[172:175], v[160:161], off offset:512 nt
	v_lshl_add_u64 v[160:161], v[160:161], 0, s[64:65]
	global_load_dwordx4 v[176:179], v[160:161], off offset:512 nt
	v_lshl_add_u64 v[160:161], v[160:161], 0, s[64:65]
	global_load_dwordx4 v[180:183], v[160:161], off offset:512 nt
	v_lshl_add_u64 v[160:161], v[160:161], 0, s[64:65]
	global_load_dwordx4 v[184:187], v[160:161], off offset:512 nt
	v_lshl_add_u64 v[160:161], v[160:161], 0, s[64:65]
	global_load_dwordx4 v[188:191], v[160:161], off offset:512 nt
	v_lshl_add_u64 v[160:161], v[160:161], 0, s[64:65]
	global_load_dwordx4 v[192:195], v[160:161], off offset:512 nt
	v_lshl_add_u64 v[160:161], v[160:161], 0, s[64:65]
	global_load_dwordx4 v[196:199], v[160:161], off offset:512 nt
	s_waitcnt vmcnt(24)
	v_cvt_pk_bf16_f32 v236, v204, v208
	v_cvt_pk_bf16_f32 v237, v212, v216
	v_cvt_pk_bf16_f32 v238, v220, v224
	v_cvt_pk_bf16_f32 v239, v228, v232
	v_cvt_pk_bf16_f32 v244, v205, v209
	v_cvt_pk_bf16_f32 v245, v213, v217
	v_cvt_pk_bf16_f32 v246, v221, v225
	v_cvt_pk_bf16_f32 v247, v229, v233
	global_store_dwordx4 v[166:167], v[236:239], off
	v_lshl_add_u64 v[202:203], v[166:167], 0, s[66:67]
	global_store_dwordx4 v[202:203], v[244:247], off
	s_nop 1
	v_cvt_pk_bf16_f32 v236, v206, v210
	v_cvt_pk_bf16_f32 v237, v214, v218
	v_cvt_pk_bf16_f32 v238, v222, v226
	v_cvt_pk_bf16_f32 v239, v230, v234
	v_cvt_pk_bf16_f32 v244, v207, v211
	v_cvt_pk_bf16_f32 v245, v215, v219
	v_cvt_pk_bf16_f32 v246, v223, v227
	v_cvt_pk_bf16_f32 v247, v231, v235
	v_lshl_add_u64 v[202:203], v[166:167], 0, s[68:69]
	global_store_dwordx4 v[202:203], v[236:239], off
	v_lshl_add_u64 v[202:203], v[166:167], 0, s[70:71]
	global_store_dwordx4 v[202:203], v[244:247], off
	v_lshl_add_u64 v[166:167], v[166:167], 0, s[72:73]
	v_mov_b64_e32 v[160:161], v[240:241]
	global_load_dwordx4 v[204:207], v[160:161], off offset:640 nt
	v_lshl_add_u64 v[160:161], v[160:161], 0, s[64:65]
	global_load_dwordx4 v[208:211], v[160:161], off offset:640 nt
	v_lshl_add_u64 v[160:161], v[160:161], 0, s[64:65]
	global_load_dwordx4 v[212:215], v[160:161], off offset:640 nt
	v_lshl_add_u64 v[160:161], v[160:161], 0, s[64:65]
	global_load_dwordx4 v[216:219], v[160:161], off offset:640 nt
	v_lshl_add_u64 v[160:161], v[160:161], 0, s[64:65]
	global_load_dwordx4 v[220:223], v[160:161], off offset:640 nt
	v_lshl_add_u64 v[160:161], v[160:161], 0, s[64:65]
	global_load_dwordx4 v[224:227], v[160:161], off offset:640 nt
	v_lshl_add_u64 v[160:161], v[160:161], 0, s[64:65]
	global_load_dwordx4 v[228:231], v[160:161], off offset:640 nt
	v_lshl_add_u64 v[160:161], v[160:161], 0, s[64:65]
	global_load_dwordx4 v[232:235], v[160:161], off offset:640 nt
	s_waitcnt vmcnt(24)
	v_cvt_pk_bf16_f32 v236, v128, v132
	v_cvt_pk_bf16_f32 v237, v136, v140
	v_cvt_pk_bf16_f32 v238, v144, v148
	v_cvt_pk_bf16_f32 v239, v152, v156
	v_cvt_pk_bf16_f32 v244, v129, v133
	v_cvt_pk_bf16_f32 v245, v137, v141
	v_cvt_pk_bf16_f32 v246, v145, v149
	v_cvt_pk_bf16_f32 v247, v153, v157
	global_store_dwordx4 v[166:167], v[236:239], off
	v_lshl_add_u64 v[202:203], v[166:167], 0, s[66:67]
	global_store_dwordx4 v[202:203], v[244:247], off
	s_nop 1
	v_cvt_pk_bf16_f32 v236, v130, v134
	v_cvt_pk_bf16_f32 v237, v138, v142
	v_cvt_pk_bf16_f32 v238, v146, v150
	v_cvt_pk_bf16_f32 v239, v154, v158
	v_cvt_pk_bf16_f32 v244, v131, v135
	v_cvt_pk_bf16_f32 v245, v139, v143
	v_cvt_pk_bf16_f32 v246, v147, v151
	v_cvt_pk_bf16_f32 v247, v155, v159
	v_lshl_add_u64 v[202:203], v[166:167], 0, s[68:69]
	global_store_dwordx4 v[202:203], v[236:239], off
	v_lshl_add_u64 v[202:203], v[166:167], 0, s[70:71]
	global_store_dwordx4 v[202:203], v[244:247], off
	v_lshl_add_u64 v[166:167], v[166:167], 0, s[72:73]
	v_mov_b64_e32 v[160:161], v[240:241]
	global_load_dwordx4 v[128:131], v[160:161], off offset:768 nt
	v_lshl_add_u64 v[160:161], v[160:161], 0, s[64:65]
	global_load_dwordx4 v[132:135], v[160:161], off offset:768 nt
	v_lshl_add_u64 v[160:161], v[160:161], 0, s[64:65]
	global_load_dwordx4 v[136:139], v[160:161], off offset:768 nt
	v_lshl_add_u64 v[160:161], v[160:161], 0, s[64:65]
	global_load_dwordx4 v[140:143], v[160:161], off offset:768 nt
	v_lshl_add_u64 v[160:161], v[160:161], 0, s[64:65]
	global_load_dwordx4 v[144:147], v[160:161], off offset:768 nt
	v_lshl_add_u64 v[160:161], v[160:161], 0, s[64:65]
	global_load_dwordx4 v[148:151], v[160:161], off offset:768 nt
	v_lshl_add_u64 v[160:161], v[160:161], 0, s[64:65]
	global_load_dwordx4 v[152:155], v[160:161], off offset:768 nt
	v_lshl_add_u64 v[160:161], v[160:161], 0, s[64:65]
	global_load_dwordx4 v[156:159], v[160:161], off offset:768 nt
	s_waitcnt vmcnt(24)
	v_cvt_pk_bf16_f32 v236, v168, v172
	v_cvt_pk_bf16_f32 v237, v176, v180
	v_cvt_pk_bf16_f32 v238, v184, v188
	v_cvt_pk_bf16_f32 v239, v192, v196
	v_cvt_pk_bf16_f32 v244, v169, v173
	v_cvt_pk_bf16_f32 v245, v177, v181
	v_cvt_pk_bf16_f32 v246, v185, v189
	v_cvt_pk_bf16_f32 v247, v193, v197
	global_store_dwordx4 v[166:167], v[236:239], off
	v_lshl_add_u64 v[202:203], v[166:167], 0, s[66:67]
	global_store_dwordx4 v[202:203], v[244:247], off
	s_nop 1
	v_cvt_pk_bf16_f32 v236, v170, v174
	v_cvt_pk_bf16_f32 v237, v178, v182
	v_cvt_pk_bf16_f32 v238, v186, v190
	v_cvt_pk_bf16_f32 v239, v194, v198
	v_cvt_pk_bf16_f32 v244, v171, v175
	v_cvt_pk_bf16_f32 v245, v179, v183
	v_cvt_pk_bf16_f32 v246, v187, v191
	v_cvt_pk_bf16_f32 v247, v195, v199
	v_lshl_add_u64 v[202:203], v[166:167], 0, s[68:69]
	global_store_dwordx4 v[202:203], v[236:239], off
	v_lshl_add_u64 v[202:203], v[166:167], 0, s[70:71]
	global_store_dwordx4 v[202:203], v[244:247], off
	v_lshl_add_u64 v[166:167], v[166:167], 0, s[72:73]
	v_mov_b64_e32 v[160:161], v[240:241]
	global_load_dwordx4 v[168:171], v[160:161], off offset:896 nt
	v_lshl_add_u64 v[160:161], v[160:161], 0, s[64:65]
	global_load_dwordx4 v[172:175], v[160:161], off offset:896 nt
	v_lshl_add_u64 v[160:161], v[160:161], 0, s[64:65]
	global_load_dwordx4 v[176:179], v[160:161], off offset:896 nt
	v_lshl_add_u64 v[160:161], v[160:161], 0, s[64:65]
	global_load_dwordx4 v[180:183], v[160:161], off offset:896 nt
	v_lshl_add_u64 v[160:161], v[160:161], 0, s[64:65]
	global_load_dwordx4 v[184:187], v[160:161], off offset:896 nt
	v_lshl_add_u64 v[160:161], v[160:161], 0, s[64:65]
	global_load_dwordx4 v[188:191], v[160:161], off offset:896 nt
	v_lshl_add_u64 v[160:161], v[160:161], 0, s[64:65]
	global_load_dwordx4 v[192:195], v[160:161], off offset:896 nt
	v_lshl_add_u64 v[160:161], v[160:161], 0, s[64:65]
	global_load_dwordx4 v[196:199], v[160:161], off offset:896 nt
	s_waitcnt vmcnt(24)
	v_cvt_pk_bf16_f32 v236, v204, v208
	v_cvt_pk_bf16_f32 v237, v212, v216
	v_cvt_pk_bf16_f32 v238, v220, v224
	v_cvt_pk_bf16_f32 v239, v228, v232
	v_cvt_pk_bf16_f32 v244, v205, v209
	v_cvt_pk_bf16_f32 v245, v213, v217
	v_cvt_pk_bf16_f32 v246, v221, v225
	v_cvt_pk_bf16_f32 v247, v229, v233
	global_store_dwordx4 v[166:167], v[236:239], off
	v_lshl_add_u64 v[202:203], v[166:167], 0, s[66:67]
	global_store_dwordx4 v[202:203], v[244:247], off
	s_nop 1
	v_cvt_pk_bf16_f32 v236, v206, v210
	v_cvt_pk_bf16_f32 v237, v214, v218
	v_cvt_pk_bf16_f32 v238, v222, v226
	v_cvt_pk_bf16_f32 v239, v230, v234
	v_cvt_pk_bf16_f32 v244, v207, v211
	v_cvt_pk_bf16_f32 v245, v215, v219
	v_cvt_pk_bf16_f32 v246, v223, v227
	v_cvt_pk_bf16_f32 v247, v231, v235
	v_lshl_add_u64 v[202:203], v[166:167], 0, s[68:69]
	global_store_dwordx4 v[202:203], v[236:239], off
	v_lshl_add_u64 v[202:203], v[166:167], 0, s[70:71]
	global_store_dwordx4 v[202:203], v[244:247], off
	v_lshl_add_u64 v[166:167], v[166:167], 0, s[72:73]
	s_waitcnt vmcnt(16)
	v_cvt_pk_bf16_f32 v236, v128, v132
	v_cvt_pk_bf16_f32 v237, v136, v140
	v_cvt_pk_bf16_f32 v238, v144, v148
	v_cvt_pk_bf16_f32 v239, v152, v156
	v_cvt_pk_bf16_f32 v244, v129, v133
	v_cvt_pk_bf16_f32 v245, v137, v141
	v_cvt_pk_bf16_f32 v246, v145, v149
	v_cvt_pk_bf16_f32 v247, v153, v157
	global_store_dwordx4 v[166:167], v[236:239], off
	v_lshl_add_u64 v[202:203], v[166:167], 0, s[66:67]
	global_store_dwordx4 v[202:203], v[244:247], off
	s_nop 1
	v_cvt_pk_bf16_f32 v236, v130, v134
	v_cvt_pk_bf16_f32 v237, v138, v142
	v_cvt_pk_bf16_f32 v238, v146, v150
	v_cvt_pk_bf16_f32 v239, v154, v158
	v_cvt_pk_bf16_f32 v244, v131, v135
	v_cvt_pk_bf16_f32 v245, v139, v143
	v_cvt_pk_bf16_f32 v246, v147, v151
	v_cvt_pk_bf16_f32 v247, v155, v159
	v_lshl_add_u64 v[202:203], v[166:167], 0, s[68:69]
	global_store_dwordx4 v[202:203], v[236:239], off
	v_lshl_add_u64 v[202:203], v[166:167], 0, s[70:71]
	global_store_dwordx4 v[202:203], v[244:247], off
	v_lshl_add_u64 v[166:167], v[166:167], 0, s[72:73]
	s_waitcnt vmcnt(8)
	v_cvt_pk_bf16_f32 v236, v168, v172
	v_cvt_pk_bf16_f32 v237, v176, v180
	v_cvt_pk_bf16_f32 v238, v184, v188
	v_cvt_pk_bf16_f32 v239, v192, v196
	v_cvt_pk_bf16_f32 v244, v169, v173
	v_cvt_pk_bf16_f32 v245, v177, v181
	v_cvt_pk_bf16_f32 v246, v185, v189
	v_cvt_pk_bf16_f32 v247, v193, v197
	global_store_dwordx4 v[166:167], v[236:239], off
	v_lshl_add_u64 v[202:203], v[166:167], 0, s[66:67]
	global_store_dwordx4 v[202:203], v[244:247], off
	s_nop 1
	v_cvt_pk_bf16_f32 v236, v170, v174
	v_cvt_pk_bf16_f32 v237, v178, v182
	v_cvt_pk_bf16_f32 v238, v186, v190
	v_cvt_pk_bf16_f32 v239, v194, v198
	v_cvt_pk_bf16_f32 v244, v171, v175
	v_cvt_pk_bf16_f32 v245, v179, v183
	v_cvt_pk_bf16_f32 v246, v187, v191
	v_cvt_pk_bf16_f32 v247, v195, v199
	v_lshl_add_u64 v[202:203], v[166:167], 0, s[68:69]
	global_store_dwordx4 v[202:203], v[236:239], off
	v_lshl_add_u64 v[202:203], v[166:167], 0, s[70:71]
	global_store_dwordx4 v[202:203], v[244:247], off
	v_lshl_add_u64 v[166:167], v[166:167], 0, s[72:73]
	s_addk_i32 s98, 0xc0
	s_cmp_lt_u32 s98, 576
	s_cbranch_scc1 .Ltr7_loop
